# speedup vs baseline: 1.0281x; 1.0281x over previous
.LBB0_1411:
	s_or_b64 exec, exec, s[0:1]
	s_cmpk_gt_i32 s79, 0x57
	s_cselect_b64 s[2:3], -1, 0
	s_xor_b64 s[4:5], s[8:9], -1
	s_or_b64 s[2:3], s[2:3], s[4:5]
	s_mov_b64 s[0:1], -1
	s_and_b64 vcc, exec, s[2:3]
	s_barrier
	s_cbranch_vccz .LBB0_1415
	s_movk_i32 s33, 0xcc0
	s_andn2_b64 vcc, exec, s[8:9]
	s_mov_b32 s52, s77
	s_cbranch_vccnz .LBB0_1414
	s_add_i32 s36, s79, 0xffffffa8
	s_movk_i32 s52, 0xa8
	s_movk_i32 s33, 0x8f8
	s_cmp_lt_u32 s36, 24
	s_cselect_b32 s33, 0x7e0, s33
	s_cmp_gt_u32 s36, 0x6f
	s_cselect_b32 s33, 0x928, s33

.LBB0_1686:
	s_add_i32 s36, s79, 0xce0
	s_movk_i32 s52, 0x58
	s_movk_i32 s33, 0x10a8
	s_waitcnt vmcnt(0)
	s_barrier

.LBB0_1690:
	s_and_b32 s98, s36, 7
	s_mul_i32 s98, s98, 24
	s_lshr_b32 s99, s36, 3
	s_add_i32 s98, s98, s99
	s_mul_hi_i32 s0, s98, 0x55555556
	s_lshr_b32 s2, s0, 31
	s_add_i32 s0, s0, s2
	s_mul_i32 s2, s0, 3
	s_and_b32 s30, s0, 7
	s_and_b32 s31, s0, -8
	s_sub_i32 s10, s98, s2
	s_or_b32 s2, s31, s30
	s_add_i32 s12, s2, 0x2000
	s_lshl_b32 s2, s10, 12
	s_ashr_i32 s13, s12, 31
	s_ashr_i32 s3, s2, 31
	s_mul_i32 s5, s12, 0x6000
	v_mov_b32_e32 v126, v244
	s_mul_hi_i32 s4, s12, 0x6000
	s_add_u32 s5, s80, s5
	s_addc_u32 s4, s81, s4
	v_ashrrev_i32_e32 v108, 6, v126
	s_lshl_b64 s[2:3], s[2:3], 1
	v_lshlrev_b32_e32 v102, 9, v108
	s_add_u32 s2, s5, s2
	v_and_b32_e32 v125, 63, v126
	s_addc_u32 s3, s4, s3
	v_ashrrev_i32_e32 v103, 31, v102
	v_lshl_add_u64 v[0:1], v[102:103], 1, s[2:3]
	v_lshlrev_b32_e32 v98, 1, v125
	v_lshl_add_u64 v[0:1], v[0:1], 0, v[98:99]
	global_load_ushort v2, v[0:1], off
	global_load_ushort v3, v[0:1], off offset:128
	global_load_ushort v4, v[0:1], off offset:256
	global_load_ushort v5, v[0:1], off offset:384
	global_load_ushort v6, v[0:1], off offset:512
	global_load_ushort v7, v[0:1], off offset:640
	global_load_ushort v8, v[0:1], off offset:768
	s_nop 0
	global_load_ushort v0, v[0:1], off offset:896
	v_mov_b32_e32 v101, v100
	v_lshlrev_b32_e32 v127, 13, v108
	v_ashrrev_i32_e32 v109, 31, v108
	s_lshl_b32 s0, s0, 8
	v_mov_b32_e32 v128, 0xff61b1e6
	v_mov_b32_e32 v130, 0xff61b1e6
	v_mov_b32_e32 v132, 0xff61b1e6
	v_mov_b32_e32 v129, 0xff61b1e6
	v_mov_b32_e32 v131, 0xff61b1e6
	v_mov_b32_e32 v133, 0xff61b1e6
	s_mov_b32 s11, s1
	v_mov_b32_e32 v134, 0xff61b1e6
	v_mov_b32_e32 v135, 0xff61b1e6
	v_mov_b64_e32 v[106:107], v[100:101]
	v_cmp_eq_u32_e64 s[2:3], 0, v125
	v_lshl_or_b32 v1, v125, 2, v127
	v_lshlrev_b64 v[104:105], 9, v[108:109]
	s_lshl_b32 s27, s10, 1
	s_bitset1_b32 s30, 11
	s_addk_i32 s31, 0xf800
	s_and_b32 s34, s0, 0xfffff800
	v_mov_b64_e32 v[110:111], v[100:101]
	s_waitcnt vmcnt(7)
	v_lshlrev_b32_e32 v2, 16, v2
	s_waitcnt vmcnt(6)
	v_lshlrev_b32_e32 v3, 16, v3
	s_waitcnt vmcnt(5)
	v_lshlrev_b32_e32 v4, 16, v4
	s_waitcnt vmcnt(4)
	v_lshlrev_b32_e32 v5, 16, v5
	s_waitcnt vmcnt(3)
	v_lshlrev_b32_e32 v6, 16, v6
	s_waitcnt vmcnt(2)
	v_lshlrev_b32_e32 v7, 16, v7
	s_waitcnt vmcnt(1)
	v_lshlrev_b32_e32 v8, 16, v8
	s_waitcnt vmcnt(0)
	v_lshlrev_b32_e32 v0, 16, v0
	ds_write2st64_b32 v1, v2, v3 offset1:1
	ds_write2st64_b32 v1, v4, v5 offset0:2 offset1:3
	ds_write2st64_b32 v1, v6, v7 offset0:4 offset1:5
	ds_write2st64_b32 v1, v8, v0 offset0:6 offset1:7
	s_waitcnt lgkmcnt(0)
	s_barrier
	s_branch .LBB0_1692

.LBB0_1727:
	s_waitcnt vmcnt(1)
	v_mov_b32_e32 v52, v244
	v_mov_b32_e32 v0, 0
	s_andn2_b64 vcc, exec, s[2:3]
	v_lshlrev_b32_e32 v53, 4, v52
	v_ashrrev_i32_e32 v110, 4, v52
	v_mov_b32_e32 v1, 0
	v_mov_b32_e32 v2, 0
	v_mov_b32_e32 v3, 0
	v_mov_b32_e32 v4, 0
	v_mov_b32_e32 v5, 0
	v_mov_b32_e32 v6, 0
	v_mov_b32_e32 v7, 0
	v_mov_b32_e32 v8, 0
	v_mov_b32_e32 v9, 0
	v_mov_b32_e32 v10, 0
	v_mov_b32_e32 v11, 0
	v_mov_b32_e32 v12, 0
	v_mov_b32_e32 v13, 0
	v_mov_b32_e32 v14, 0
	v_mov_b32_e32 v15, 0
	v_mov_b32_e32 v16, 0
	v_mov_b32_e32 v17, 0
	v_mov_b32_e32 v18, 0
	v_mov_b32_e32 v19, 0
	v_mov_b32_e32 v20, 0
	v_mov_b32_e32 v21, 0
	v_mov_b32_e32 v22, 0
	v_mov_b32_e32 v23, 0
	v_mov_b32_e32 v24, 0
	v_mov_b32_e32 v25, 0
	v_mov_b32_e32 v26, 0
	v_mov_b32_e32 v27, 0
	v_mov_b32_e32 v28, 0
	v_mov_b32_e32 v29, 0
	v_mov_b32_e32 v30, 0
	v_mov_b32_e32 v31, 0
	v_mov_b32_e32 v32, 0
	v_mov_b32_e32 v33, 0
	v_mov_b32_e32 v34, 0
	v_mov_b32_e32 v35, 0
	v_mov_b32_e32 v36, 0
	v_mov_b32_e32 v37, 0
	v_mov_b32_e32 v38, 0
	v_mov_b32_e32 v39, 0
	v_mov_b32_e32 v40, 0
	v_mov_b32_e32 v41, 0
	v_mov_b32_e32 v42, 0
	v_mov_b32_e32 v43, 0
	v_mov_b32_e32 v44, 0
	v_mov_b32_e32 v45, 0
	v_mov_b32_e32 v46, 0
	v_mov_b32_e32 v47, 0
	s_waitcnt vmcnt(0)
	v_mov_b32_e32 v48, 0
	v_mov_b32_e32 v49, 0
	v_mov_b32_e32 v50, 0
	v_mov_b32_e32 v51, 0
	s_cbranch_vccnz .LBB0_1729
	s_add_i32 s98, s36, 0xfffffee8
	s_cmpk_lt_i32 s36, 0x8f8
	s_cselect_b32 s98, s36, s98
	s_add_i32 s99, s36, 0xffffff78
	s_cmpk_lt_i32 s36, 0x910
	s_cselect_b32 s98, s98, s99
	s_add_i32 s99, s36, 0xfffffc18
	s_cmpk_lt_i32 s36, 0xce0
	s_cselect_b32 s98, s98, s99
	s_add_i32 s0, s98, 0xffffff40
	s_ashr_i32 s0, s0, 5
	s_mul_hi_i32 s2, s0, 0x55555556
	s_lshr_b32 s3, s2, 31
	s_add_i32 s3, s2, s3
	s_mul_i32 s2, s3, 3
	s_sub_i32 s0, s0, s2
	s_lshl_b32 s6, s0, 1
	s_lshr_b32 s2, 32, s6
	s_and_b32 s1, s98, 31
	s_sub_i32 s5, 5, s6
	s_add_i32 s2, s2, -1
	s_lshr_b32 s5, s1, s5
	s_and_b32 s1, s2, s1
	s_lshl_b32 s2, s1, 6
	s_lshl_b32 s0, s0, 5
	s_and_b32 s1, s3, -8
	s_and_b32 s4, s3, 7
	s_add_i32 s0, s0, s1
	s_or_b32 s0, s0, s4
	s_lshl_b32 s3, s3, 8
	s_ashr_i32 s1, s0, 31
	s_and_b32 s3, s3, 0xfffff800
	s_lshr_b32 s7, 0x800, s6
	s_lshl_b64 s[0:1], s[0:1], 19
	s_addk_i32 s2, 0xff80
	s_or_b32 s3, s5, s3
	s_lshl_b32 s4, s4, 8
	v_readlane_b32 s10, v249, 10
	v_readlane_b32 s11, v249, 11
	s_add_u32 s4, s10, s4
	s_mul_i32 s8, s5, s7
	s_addc_u32 s5, s11, 0
	v_and_b32_e32 v0, 0xf0, v53
	v_mov_b32_e32 v1, 0
	v_lshl_add_u64 v[16:17], s[4:5], 0, v[0:1]
	v_add_u32_e32 v0, s2, v110
	v_max_i32_e32 v0, 0, v0
	v_lshlrev_b32_e32 v0, s6, v0
	v_add_u32_e32 v0, s3, v0
	v_ashrrev_i32_e32 v1, 31, v0
	v_lshlrev_b64 v[0:1], 11, v[0:1]
	v_add_u32_e32 v28, 0x200, v52
	v_lshl_add_u64 v[8:9], v[16:17], 0, v[0:1]
	v_ashrrev_i32_e32 v0, 4, v28
	v_add_u32_e32 v0, s2, v0
	v_max_i32_e32 v0, 0, v0
	v_lshlrev_b32_e32 v0, s6, v0
	v_add_u32_e32 v0, s3, v0
	v_ashrrev_i32_e32 v1, 31, v0
	v_lshlrev_b64 v[0:1], 11, v[0:1]
	v_add_u32_e32 v36, 0x400, v52
	v_lshl_add_u64 v[10:11], v[16:17], 0, v[0:1]
	global_load_dwordx4 v[0:3], v[8:9], off
	global_load_dwordx4 v[4:7], v[10:11], off
	v_ashrrev_i32_e32 v8, 4, v36
	v_add_u32_e32 v8, s2, v8
	v_max_i32_e32 v8, 0, v8
	v_lshlrev_b32_e32 v8, s6, v8
	v_add_u32_e32 v8, s3, v8
	v_ashrrev_i32_e32 v9, 31, v8
	v_lshlrev_b64 v[8:9], 11, v[8:9]
	v_add_u32_e32 v37, 0x600, v52
	v_lshl_add_u64 v[18:19], v[16:17], 0, v[8:9]
	v_ashrrev_i32_e32 v8, 4, v37
	v_add_u32_e32 v8, s2, v8
	v_max_i32_e32 v8, 0, v8
	v_lshlrev_b32_e32 v8, s6, v8
	v_add_u32_e32 v8, s3, v8
	v_ashrrev_i32_e32 v9, 31, v8
	v_lshlrev_b64 v[8:9], 11, v[8:9]
	v_add_u32_e32 v44, 0x800, v52
	v_lshl_add_u64 v[20:21], v[16:17], 0, v[8:9]
	global_load_dwordx4 v[8:11], v[18:19], off
	global_load_dwordx4 v[12:15], v[20:21], off
	v_ashrrev_i32_e32 v18, 4, v44
	v_add_u32_e32 v18, s2, v18
	v_max_i32_e32 v18, 0, v18
	v_lshlrev_b32_e32 v18, s6, v18
	v_add_u32_e32 v18, s3, v18
	v_ashrrev_i32_e32 v19, 31, v18
	v_lshlrev_b64 v[18:19], 11, v[18:19]
	v_add_u32_e32 v45, 0xa00, v52
	v_lshl_add_u64 v[24:25], v[16:17], 0, v[18:19]
	v_ashrrev_i32_e32 v18, 4, v45
	v_add_u32_e32 v18, s2, v18
	v_max_i32_e32 v18, 0, v18
	v_lshlrev_b32_e32 v18, s6, v18
	v_add_u32_e32 v18, s3, v18
	v_ashrrev_i32_e32 v19, 31, v18
	s_add_u32 s0, s85, s0
	v_lshlrev_b64 v[18:19], 11, v[18:19]
	s_addc_u32 s1, s86, s1
	s_lshl_b32 s3, s8, 1
	v_lshl_add_u64 v[26:27], v[16:17], 0, v[18:19]
	global_load_dwordx4 v[16:19], v[24:25], off
	global_load_dwordx4 v[20:23], v[26:27], off
	s_add_u32 s0, s0, s3
	v_min_i32_e32 v25, 0xcff, v52
	s_mov_b32 s3, 0x4ec4ec4f
	v_mul_hi_i32 v24, v25, s3
	v_lshrrev_b32_e32 v26, 31, v24
	v_ashrrev_i32_e32 v24, 3, v24
	v_add_u32_e32 v24, v24, v26
	v_mul_lo_u32 v26, v24, 26
	v_sub_u32_e32 v25, v25, v26
	v_lshl_add_u32 v25, v25, 3, s2
	s_addc_u32 s1, s1, 0
	s_add_i32 s7, s7, -8
	v_max_i32_e32 v25, 0, v25
	v_min_i32_e32 v26, s7, v25
	v_ashrrev_i32_e32 v25, 31, v24
	v_lshlrev_b64 v[24:25], 12, v[24:25]
	v_lshl_add_u64 v[24:25], s[0:1], 0, v[24:25]
	v_ashrrev_i32_e32 v27, 31, v26
	v_lshl_add_u64 v[32:33], v[26:27], 1, v[24:25]
	v_min_i32_e32 v25, 0xcff, v28
	v_mul_hi_i32 v24, v25, s3
	v_lshrrev_b32_e32 v26, 31, v24
	v_ashrrev_i32_e32 v24, 3, v24
	v_add_u32_e32 v24, v24, v26
	v_mul_lo_u32 v26, v24, 26
	v_sub_u32_e32 v25, v25, v26
	v_lshl_add_u32 v25, v25, 3, s2
	v_max_i32_e32 v25, 0, v25
	v_min_i32_e32 v26, s7, v25
	v_ashrrev_i32_e32 v25, 31, v24
	v_lshlrev_b64 v[24:25], 12, v[24:25]
	v_lshl_add_u64 v[24:25], s[0:1], 0, v[24:25]
	v_ashrrev_i32_e32 v27, 31, v26
	v_lshl_add_u64 v[34:35], v[26:27], 1, v[24:25]
	global_load_dwordx4 v[24:27], v[32:33], off
	global_load_dwordx4 v[28:31], v[34:35], off
	v_min_i32_e32 v33, 0xcff, v36
	v_mul_hi_i32 v32, v33, s3
	v_lshrrev_b32_e32 v34, 31, v32
	v_ashrrev_i32_e32 v32, 3, v32
	v_add_u32_e32 v32, v32, v34
	v_mul_lo_u32 v34, v32, 26
	v_sub_u32_e32 v33, v33, v34
	v_lshl_add_u32 v33, v33, 3, s2
	v_max_i32_e32 v33, 0, v33
	v_min_i32_e32 v34, s7, v33
	v_ashrrev_i32_e32 v33, 31, v32
	v_lshlrev_b64 v[32:33], 12, v[32:33]
	v_lshl_add_u64 v[32:33], s[0:1], 0, v[32:33]
	v_ashrrev_i32_e32 v35, 31, v34
	v_lshl_add_u64 v[40:41], v[34:35], 1, v[32:33]
	v_min_i32_e32 v33, 0xcff, v37
	v_mul_hi_i32 v32, v33, s3
	v_lshrrev_b32_e32 v34, 31, v32
	v_ashrrev_i32_e32 v32, 3, v32
	v_add_u32_e32 v32, v32, v34
	v_mul_lo_u32 v34, v32, 26
	v_sub_u32_e32 v33, v33, v34
	v_lshl_add_u32 v33, v33, 3, s2
	v_max_i32_e32 v33, 0, v33
	v_min_i32_e32 v34, s7, v33
	v_ashrrev_i32_e32 v33, 31, v32
	v_lshlrev_b64 v[32:33], 12, v[32:33]
	v_lshl_add_u64 v[32:33], s[0:1], 0, v[32:33]
	v_ashrrev_i32_e32 v35, 31, v34
	v_lshl_add_u64 v[42:43], v[34:35], 1, v[32:33]
	global_load_dwordx4 v[32:35], v[40:41], off
	global_load_dwordx4 v[36:39], v[42:43], off
	v_min_i32_e32 v41, 0xcff, v44
	v_mul_hi_i32 v40, v41, s3
	v_lshrrev_b32_e32 v42, 31, v40
	v_ashrrev_i32_e32 v40, 3, v40
	v_add_u32_e32 v40, v40, v42
	v_mul_lo_u32 v42, v40, 26
	v_sub_u32_e32 v41, v41, v42
	v_lshl_add_u32 v41, v41, 3, s2
	v_max_i32_e32 v41, 0, v41
	v_min_i32_e32 v42, s7, v41
	v_ashrrev_i32_e32 v41, 31, v40
	v_lshlrev_b64 v[40:41], 12, v[40:41]
	v_lshl_add_u64 v[40:41], s[0:1], 0, v[40:41]
	v_ashrrev_i32_e32 v43, 31, v42
	v_lshl_add_u64 v[48:49], v[42:43], 1, v[40:41]
	v_min_i32_e32 v41, 0xcff, v45
	v_mul_hi_i32 v40, v41, s3
	v_lshrrev_b32_e32 v42, 31, v40
	v_ashrrev_i32_e32 v40, 3, v40
	v_add_u32_e32 v40, v40, v42
	v_mul_lo_u32 v42, v40, 26
	v_sub_u32_e32 v41, v41, v42
	v_lshl_add_u32 v41, v41, 3, s2
	v_max_i32_e32 v41, 0, v41
	v_min_i32_e32 v42, s7, v41
	v_ashrrev_i32_e32 v41, 31, v40
	v_lshlrev_b64 v[40:41], 12, v[40:41]
	v_lshl_add_u64 v[40:41], s[0:1], 0, v[40:41]
	v_ashrrev_i32_e32 v43, 31, v42
	v_lshl_add_u64 v[50:51], v[42:43], 1, v[40:41]
	global_load_dwordx4 v[40:43], v[48:49], off
	global_load_dwordx4 v[44:47], v[50:51], off
	v_min_i32_e32 v48, 0xff, v52
	v_add_u32_e32 v49, 0xc00, v48
	v_mul_hi_i32 v48, v49, s3
	v_lshrrev_b32_e32 v50, 31, v48
	v_ashrrev_i32_e32 v48, 3, v48
	v_add_u32_e32 v48, v48, v50
	v_mul_lo_u32 v50, v48, 26
	v_sub_u32_e32 v49, v49, v50
	v_lshl_add_u32 v49, v49, 3, s2
	v_max_i32_e32 v49, 0, v49
	v_min_i32_e32 v50, s7, v49
	v_ashrrev_i32_e32 v49, 31, v48
	v_lshlrev_b64 v[48:49], 12, v[48:49]
	v_lshl_add_u64 v[48:49], s[0:1], 0, v[48:49]
	v_ashrrev_i32_e32 v51, 31, v50
	v_lshl_add_u64 v[48:49], v[50:51], 1, v[48:49]
	global_load_dwordx4 v[48:51], v[48:49], off

.LBB0_1732:
	s_waitcnt vmcnt(40)
	v_lshrrev_b32_e32 v52, 16, v27
	v_lshrrev_b32_e32 v53, 16, v26
	v_lshrrev_b32_e32 v54, 16, v25
	v_lshrrev_b32_e32 v55, 16, v24
	s_barrier
	ds_write_b128 v123, v[0:3]
	ds_write_b128 v124, v[4:7]
	ds_write_b128 v125, v[8:11]
	ds_write_b128 v126, v[12:15]
	ds_write_b128 v127, v[16:19]
	ds_write_b128 v128, v[20:23]
	s_and_saveexec_b64 s[16:17], s[2:3]
	v_perm_b32 v56, v55, v24, s60
	v_perm_b32 v57, v54, v25, s60
	v_perm_b32 v58, v53, v26, s60
	v_perm_b32 v59, v52, v27, s60
	ds_write_b128 v129, v[56:59] offset:52224
	s_or_b64 exec, exec, s[16:17]
	v_lshrrev_b32_e32 v56, 16, v31
	v_lshrrev_b32_e32 v57, 16, v30
	v_lshrrev_b32_e32 v58, 16, v29
	v_lshrrev_b32_e32 v59, 16, v28
	s_and_saveexec_b64 s[16:17], s[4:5]
	v_perm_b32 v60, v59, v28, s60
	v_perm_b32 v61, v58, v29, s60
	v_perm_b32 v62, v57, v30, s60
	v_perm_b32 v63, v56, v31, s60
	ds_write_b128 v130, v[60:63] offset:52224
	s_or_b64 exec, exec, s[16:17]
	v_lshrrev_b32_e32 v60, 16, v35
	v_lshrrev_b32_e32 v61, 16, v34
	v_lshrrev_b32_e32 v62, 16, v33
	v_lshrrev_b32_e32 v63, 16, v32
	s_and_saveexec_b64 s[16:17], s[6:7]
	v_perm_b32 v64, v63, v32, s60
	v_perm_b32 v65, v62, v33, s60
	v_perm_b32 v66, v61, v34, s60
	v_perm_b32 v67, v60, v35, s60
	ds_write_b128 v131, v[64:67] offset:52224
	s_or_b64 exec, exec, s[16:17]
	v_lshrrev_b32_e32 v64, 16, v39
	v_lshrrev_b32_e32 v65, 16, v38
	v_lshrrev_b32_e32 v66, 16, v37
	v_lshrrev_b32_e32 v67, 16, v36
	s_and_saveexec_b64 s[16:17], s[8:9]
	v_perm_b32 v68, v67, v36, s60
	v_perm_b32 v69, v66, v37, s60
	v_perm_b32 v70, v65, v38, s60
	v_perm_b32 v71, v64, v39, s60
	ds_write_b128 v132, v[68:71] offset:52224
	s_or_b64 exec, exec, s[16:17]
	v_lshrrev_b32_e32 v68, 16, v43
	v_lshrrev_b32_e32 v69, 16, v42
	v_lshrrev_b32_e32 v70, 16, v41
	v_lshrrev_b32_e32 v71, 16, v40
	s_and_saveexec_b64 s[16:17], s[10:11]
	v_perm_b32 v72, v71, v40, s60
	v_perm_b32 v73, v70, v41, s60
	v_perm_b32 v74, v69, v42, s60
	v_perm_b32 v75, v68, v43, s60
	ds_write_b128 v133, v[72:75] offset:52224
	s_or_b64 exec, exec, s[16:17]
	v_lshrrev_b32_e32 v72, 16, v47
	v_lshrrev_b32_e32 v73, 16, v46
	v_lshrrev_b32_e32 v74, 16, v45
	v_lshrrev_b32_e32 v75, 16, v44
	s_and_saveexec_b64 s[16:17], s[12:13]
	v_perm_b32 v76, v75, v44, s60
	v_perm_b32 v77, v74, v45, s60
	v_perm_b32 v78, v73, v46, s60
	v_perm_b32 v79, v72, v47, s60
	ds_write_b128 v134, v[76:79] offset:52224
	s_or_b64 exec, exec, s[16:17]
	v_lshrrev_b32_e32 v76, 16, v51
	v_lshrrev_b32_e32 v77, 16, v50
	v_lshrrev_b32_e32 v78, 16, v49
	v_lshrrev_b32_e32 v79, 16, v48
	s_and_saveexec_b64 s[16:17], s[14:15]
	v_perm_b32 v80, v79, v48, s60
	v_perm_b32 v81, v78, v49, s60
	v_perm_b32 v82, v77, v50, s60
	v_perm_b32 v83, v76, v51, s60
	ds_write_b128 v135, v[80:83] offset:52224
	s_or_b64 exec, exec, s[16:17]
	s_add_i32 s74, s36, s52
	s_cmp_ge_i32 s74, s33
	s_cselect_b64 s[48:49], -1, 0
	s_and_b64 vcc, exec, s[48:49]
	s_waitcnt lgkmcnt(0)
	s_barrier
	s_cbranch_vccnz .LBB0_1748
	s_add_i32 s98, s74, 0xfffffee8
	s_cmpk_lt_i32 s74, 0x8f8
	s_cselect_b32 s98, s74, s98
	s_add_i32 s99, s74, 0xffffff78
	s_cmpk_lt_i32 s74, 0x910
	s_cselect_b32 s98, s98, s99
	s_add_i32 s99, s74, 0xfffffc18
	s_cmpk_lt_i32 s74, 0xce0
	s_cselect_b32 s98, s98, s99
	s_add_i32 s0, s98, 0xffffff40
	s_ashr_i32 s0, s0, 5
	s_mul_hi_i32 s17, s0, 0x55555556
	s_lshr_b32 s18, s17, 31
	s_add_i32 s18, s17, s18
	s_mul_i32 s17, s18, 3
	s_sub_i32 s0, s0, s17
	s_lshl_b32 s20, s0, 1
	s_lshr_b32 s17, 32, s20
	s_and_b32 s16, s98, 31
	s_sub_i32 s22, 5, s20
	s_add_i32 s17, s17, -1
	s_lshr_b32 s22, s16, s22
	s_and_b32 s16, s17, s16
	s_lshl_b32 s23, s16, 6
	s_lshl_b32 s0, s0, 5
	s_and_b32 s16, s18, -8
	s_and_b32 s19, s18, 7
	s_add_i32 s0, s0, s16
	s_or_b32 s16, s0, s19
	s_lshl_b32 s0, s18, 8
	s_ashr_i32 s17, s16, 31
	s_and_b32 s0, s0, 0xfffff800
	s_lshr_b32 s21, 0x800, s20
	s_lshl_b64 s[16:17], s[16:17], 19
	s_addk_i32 s23, 0xff80
	s_or_b32 s18, s22, s0
	s_lshl_b32 s0, s19, 8
	s_mul_i32 s24, s22, s21
	v_lshl_add_u64 v[16:17], v[86:87], 0, s[0:1]
	s_add_u32 s0, s85, s16
	s_addc_u32 s17, s86, s17
	s_lshl_b32 s16, s24, 1
	s_add_u32 s16, s0, s16
	v_add_u32_e32 v24, s23, v116
	v_add_u32_e32 v32, s23, v118
	v_add_u32_e32 v40, s23, v120
	s_addc_u32 s17, s17, 0
	s_add_i32 s21, s21, -8
	v_max_i32_e32 v24, 0, v24
	v_max_i32_e32 v32, 0, v32
	v_max_i32_e32 v40, 0, v40
	v_add_u32_e32 v0, s23, v110
	v_add_u32_e32 v2, s23, v111
	v_add_u32_e32 v8, s23, v112
	v_add_u32_e32 v10, s23, v113
	v_add_u32_e32 v18, s23, v114
	v_add_u32_e32 v20, s23, v115
	v_min_i32_e32 v24, s21, v24
	v_min_i32_e32 v32, s21, v32
	v_min_i32_e32 v40, s21, v40
	v_max_i32_e32 v0, 0, v0
	v_max_i32_e32 v2, 0, v2
	v_max_i32_e32 v8, 0, v8
	v_max_i32_e32 v10, 0, v10
	v_max_i32_e32 v18, 0, v18
	v_max_i32_e32 v20, 0, v20
	v_lshl_add_u64 v[26:27], s[16:17], 0, v[88:89]
	v_ashrrev_i32_e32 v25, 31, v24
	v_lshl_add_u64 v[34:35], s[16:17], 0, v[92:93]
	v_ashrrev_i32_e32 v33, 31, v32
	v_lshl_add_u64 v[42:43], s[16:17], 0, v[96:97]
	v_ashrrev_i32_e32 v41, 31, v40
	v_lshlrev_b32_e32 v0, s20, v0
	v_lshlrev_b32_e32 v2, s20, v2
	v_lshlrev_b32_e32 v8, s20, v8
	v_lshlrev_b32_e32 v10, s20, v10
	v_lshlrev_b32_e32 v18, s20, v18
	v_lshlrev_b32_e32 v20, s20, v20
	v_lshl_add_u64 v[24:25], v[24:25], 1, v[26:27]
	v_add_u32_e32 v26, s23, v117
	v_lshl_add_u64 v[32:33], v[32:33], 1, v[34:35]
	v_add_u32_e32 v34, s23, v119
	v_lshl_add_u64 v[40:41], v[40:41], 1, v[42:43]
	v_add_u32_e32 v42, s23, v121
	v_add_u32_e32 v48, s23, v122
	v_add_u32_e32 v0, s18, v0
	v_add_u32_e32 v2, s18, v2
	v_add_u32_e32 v8, s18, v8
	v_add_u32_e32 v10, s18, v10
	v_add_u32_e32 v18, s18, v18
	v_add_u32_e32 v20, s18, v20
	v_max_i32_e32 v26, 0, v26
	v_max_i32_e32 v34, 0, v34
	v_max_i32_e32 v42, 0, v42
	v_max_i32_e32 v48, 0, v48
	v_ashrrev_i32_e32 v1, 31, v0
	v_ashrrev_i32_e32 v3, 31, v2
	v_ashrrev_i32_e32 v9, 31, v8
	v_ashrrev_i32_e32 v11, 31, v10
	v_ashrrev_i32_e32 v19, 31, v18
	v_ashrrev_i32_e32 v21, 31, v20
	v_min_i32_e32 v26, s21, v26
	v_min_i32_e32 v34, s21, v34
	v_min_i32_e32 v42, s21, v42
	v_min_i32_e32 v48, s21, v48
	v_lshlrev_b64 v[0:1], 11, v[0:1]
	v_lshlrev_b64 v[2:3], 11, v[2:3]
	v_lshlrev_b64 v[8:9], 11, v[8:9]
	v_lshlrev_b64 v[10:11], 11, v[10:11]
	v_lshlrev_b64 v[18:19], 11, v[18:19]
	v_lshlrev_b64 v[20:21], 11, v[20:21]
	v_lshl_add_u64 v[28:29], s[16:17], 0, v[90:91]
	v_ashrrev_i32_e32 v27, 31, v26
	v_lshl_add_u64 v[36:37], s[16:17], 0, v[94:95]
	v_ashrrev_i32_e32 v35, 31, v34
	v_lshl_add_u64 v[44:45], s[16:17], 0, v[98:99]
	v_ashrrev_i32_e32 v43, 31, v42
	v_lshl_add_u64 v[50:51], s[16:17], 0, v[100:101]
	v_ashrrev_i32_e32 v49, 31, v48
	v_lshl_add_u64 v[0:1], v[16:17], 0, v[0:1]
	v_lshl_add_u64 v[4:5], v[16:17], 0, v[2:3]
	v_lshl_add_u64 v[8:9], v[16:17], 0, v[8:9]
	v_lshl_add_u64 v[12:13], v[16:17], 0, v[10:11]
	v_lshl_add_u64 v[18:19], v[16:17], 0, v[18:19]
	v_lshl_add_u64 v[20:21], v[16:17], 0, v[20:21]
	v_lshl_add_u64 v[28:29], v[26:27], 1, v[28:29]
	v_lshl_add_u64 v[36:37], v[34:35], 1, v[36:37]
	v_lshl_add_u64 v[44:45], v[42:43], 1, v[44:45]
	v_lshl_add_u64 v[48:49], v[48:49], 1, v[50:51]
	s_branch .LBB0_1749

.LBB0_1749:
	s_add_i32 s98, s36, 0xfffffee8
	s_cmpk_lt_i32 s36, 0x8f8
	s_cselect_b32 s98, s36, s98
	s_add_i32 s99, s36, 0xffffff78
	s_cmpk_lt_i32 s36, 0x910
	s_cselect_b32 s98, s98, s99
	s_add_i32 s99, s36, 0xfffffc18
	s_cmpk_lt_i32 s36, 0xce0
	s_cselect_b32 s98, s98, s99
	s_add_i32 s0, s98, 0xffffff40
	s_ashr_i32 s0, s0, 5
	s_mul_hi_i32 s17, s0, 0x55555556
	s_lshr_b32 s18, s17, 31
	s_add_i32 s20, s17, s18
	s_mul_i32 s17, s20, 3
	s_sub_i32 s21, s0, s17
	s_lshl_b32 s0, s21, 1
	s_lshr_b32 s17, 32, s0
	v_mov_b32_e32 v52, v244
	s_and_b32 s16, s98, 31
	s_sub_i32 s18, 5, s0
	s_add_i32 s17, s17, -1
	s_lshr_b32 s22, s16, s18
	s_and_b32 s28, s17, s16
	s_lshl_b32 s16, s20, 2
	v_ashrrev_i32_e32 v53, 6, v52
	v_and_b32_e32 v138, 15, v52
	v_bfe_u32 v58, v52, 4, 2
	v_ashrrev_i32_e32 v52, 7, v52
	s_and_b32 s16, s16, 28
	s_lshl_b32 s75, s28, 6
	v_add_u32_e32 v52, s16, v52
	s_mul_i32 s16, s21, 0x4200000
	s_mul_hi_i32 s17, s21, 0x4200000
	s_add_u32 s16, s54, s16
	s_addc_u32 s17, s55, s17
	s_mul_i32 s18, s21, 0x108000
	s_mul_hi_i32 s19, s21, 0x108000
	s_add_u32 s18, s58, s18
	s_addc_u32 s19, s59, s19
	s_lshl_b32 s20, s20, 8
	s_and_b32 s20, s20, 0xfffff800
	s_or_b32 s76, s22, s20
	s_lshl_b32 s20, s21, 12
	v_mul_lo_u32 v54, v53, s61
	s_ashr_i32 s21, s20, 31
	v_add_u32_e32 v59, 0x1a400, v54
	v_lshlrev_b32_e32 v53, 5, v53
	s_lshl_b64 s[20:21], s[20:21], 1
	v_lshlrev_b32_e32 v54, 7, v52
	v_lshlrev_b32_e32 v141, 2, v58
	v_and_b32_e32 v139, 32, v53
	s_add_u32 s20, s80, s20
	v_ashrrev_i32_e32 v55, 31, v54
	v_sub_u32_e32 v60, v141, v138
	v_ashrrev_i32_e32 v53, 31, v52
	s_addc_u32 s21, s81, s21
	v_lshlrev_b64 v[54:55], 1, v[54:55]
	v_lshl_add_u64 v[106:107], v[52:53], 2, s[18:19]
	v_add_u32_e32 v52, 1, v60
	v_lshl_add_u64 v[56:57], s[20:21], 0, v[54:55]
	v_cmp_gt_u32_e64 s[20:21], s63, v52
	v_add_u32_e32 v52, 0x82, v60
	v_add_u32_e32 v61, 0x80, v60
	v_cmp_gt_u32_e64 s[34:35], s63, v52
	v_add_u32_e32 v52, 2, v60
	s_cmp_gt_u32 s28, 1
	v_cmp_gt_u32_e32 vcc, s63, v61
	v_cmp_gt_u32_e64 s[22:23], s63, v52
	v_add_u32_e32 v52, 0x83, v60
	s_cselect_b64 s[40:41], -1, 0
	v_lshlrev_b32_e32 v84, 4, v58
	v_cmp_gt_u32_e64 s[36:37], s63, v52
	v_add_u32_e32 v52, 3, v60
	s_and_b64 s[26:27], vcc, s[40:41]
	v_lshl_add_u64 v[102:103], v[56:57], 0, v[84:85]
	v_mad_u32_u24 v62, v138, s62, v59
	v_lshl_add_u64 v[54:55], s[16:17], 0, v[54:55]
	v_lshlrev_b32_e32 v56, 1, v138
	v_mov_b32_e32 v57, v85
	v_cmp_lt_u32_e64 s[30:31], s64, v60
	v_cmp_gt_u32_e64 s[24:25], s63, v52
	v_mad_u32_u24 v52, v58, s65, v59
	s_cmp_eq_u32 s28, 0
	v_lshlrev_b32_e32 v140, 3, v58
	v_lshl_add_u64 v[104:105], v[54:55], 0, v[56:57]
	s_mov_b32 s38, 0
	v_cmp_eq_u32_e64 s[16:17], 0, v138
	v_cmp_gt_u32_e64 s[18:19], s63, v60
	v_or_b32_e32 v142, v52, v56
	v_mul_u32_u24_e32 v143, 0x1b0, v138
	s_cselect_b64 s[28:29], -1, 0
	s_and_b64 s[30:31], s[30:31], s[40:41]
	s_and_b64 s[34:35], s[34:35], s[40:41]
	s_and_b64 s[36:37], s[36:37], s[40:41]
	s_mov_b64 s[50:51], -1
	v_add_u32_e32 v144, v62, v84
	s_branch .LBB0_1751
